# in-proj K loop: back edge taken before the loop-back barrier, segment 1/2/6 address arithmetic moved above the barrier in front of it
# speedup vs baseline: 1.0038x; 1.0038x over previous
; template <class Epi>
; __device__ __forceinline__ void gemm_phase(LAS unsigned char* lds, const Gemm g, const StaticOrder& S, const Epi& E, const int tid) {
;     ...
;         const bool has_next = S.next(ui + 1, nxt);
;         const char* nA = has_next ? (const char*)g.A + (size_t)nxt.pm * tstep : cA; const char* nB = has_next ? (const char*)g.Bt + (size_t)nxt.pn * tstep : cB;
;     ...
; #pragma unroll
;         for (int a = 0; a < 2; ++a)
; #pragma unroll
;             for (int b = 0; b < 2; ++b)
; #pragma unroll
;                 for (int m = 0; m < 4; ++m)
; #pragma unroll
;                     for (int n = 0; n < 2; ++n) acc[a][b][m][n] = (f32x4){0.f, 0.f, 0.f, 0.f};
;         cur = nxt; cA = nA; cB = nB; ++ui;
.LBB0_331:
	s_ashr_i32 s9, s8, 31
	v_cmp_lt_i64_e32 vcc, s[10:11], v[154:155]
	s_lshl_b64 s[10:11], s[8:9], 20
	s_add_u32 s10, s96, s10
	s_addc_u32 s11, s74, s11
	s_and_b64 s[12:13], vcc, exec
	s_cselect_b32 s9, s11, s15
	s_cselect_b32 s50, s10, s14
	s_ashr_i32 s1, s0, 31
	s_lshl_b64 s[12:13], s[0:1], 20
	s_add_u32 s12, s24, s12
	s_addc_u32 s13, s25, s13
	s_and_b64 s[22:23], vcc, exec
	s_cselect_b32 s1, s13, s19
	s_cselect_b32 s51, s12, s18
	s_add_u32 s14, s14, 0x80080
	s_addc_u32 s15, s15, 0
	s_add_u32 s52, s18, 0x100
	v_mov_b32_e32 v4, 0
	s_addc_u32 s53, s19, 0
	s_mov_b32 s54, -2
	v_mov_b32_e32 v5, v4
	v_mov_b32_e32 v6, v4
	v_mov_b32_e32 v7, v4
	v_mov_b32_e32 v8, v4
	v_mov_b32_e32 v9, v4
	v_mov_b32_e32 v10, v4
	v_mov_b32_e32 v11, v4
	v_mov_b32_e32 v24, v4
	v_mov_b32_e32 v25, v4
	v_mov_b32_e32 v26, v4
	v_mov_b32_e32 v27, v4
	v_mov_b32_e32 v20, v4
	v_mov_b32_e32 v21, v4
	v_mov_b32_e32 v22, v4
	v_mov_b32_e32 v23, v4
	v_mov_b32_e32 v40, v4
	v_mov_b32_e32 v41, v4
	v_mov_b32_e32 v42, v4
	v_mov_b32_e32 v43, v4
	v_mov_b32_e32 v36, v4
	v_mov_b32_e32 v37, v4
	v_mov_b32_e32 v38, v4
	v_mov_b32_e32 v39, v4
	v_mov_b32_e32 v56, v4
	v_mov_b32_e32 v57, v4
	v_mov_b32_e32 v58, v4
	v_mov_b32_e32 v59, v4
	v_mov_b32_e32 v52, v4
	v_mov_b32_e32 v53, v4
	v_mov_b32_e32 v54, v4
	v_mov_b32_e32 v55, v4
	v_mov_b32_e32 v16, v4
	v_mov_b32_e32 v17, v4
	v_mov_b32_e32 v18, v4
	v_mov_b32_e32 v19, v4
	v_mov_b32_e32 v12, v4
	v_mov_b32_e32 v13, v4
	v_mov_b32_e32 v14, v4
	v_mov_b32_e32 v15, v4
	v_mov_b32_e32 v32, v4
	v_mov_b32_e32 v33, v4
	v_mov_b32_e32 v34, v4
	v_mov_b32_e32 v35, v4
	v_mov_b32_e32 v28, v4
	v_mov_b32_e32 v29, v4
	v_mov_b32_e32 v30, v4
	v_mov_b32_e32 v31, v4
	v_mov_b32_e32 v48, v4
	v_mov_b32_e32 v49, v4
	v_mov_b32_e32 v50, v4
	v_mov_b32_e32 v51, v4
	v_mov_b32_e32 v44, v4
	v_mov_b32_e32 v45, v4
	v_mov_b32_e32 v46, v4
	v_mov_b32_e32 v47, v4
	v_mov_b32_e32 v64, v4
	v_mov_b32_e32 v65, v4
	v_mov_b32_e32 v66, v4
	v_mov_b32_e32 v67, v4
	v_mov_b32_e32 v60, v4
	v_mov_b32_e32 v61, v4
	v_mov_b32_e32 v62, v4
	v_mov_b32_e32 v63, v4
	v_mov_b32_e32 v72, v4
	v_mov_b32_e32 v73, v4
	v_mov_b32_e32 v74, v4
	v_mov_b32_e32 v75, v4
	v_mov_b32_e32 v68, v4
	v_mov_b32_e32 v69, v4
	v_mov_b32_e32 v70, v4
	v_mov_b32_e32 v71, v4
	v_mov_b32_e32 v88, v4
	v_mov_b32_e32 v89, v4
	v_mov_b32_e32 v90, v4
	v_mov_b32_e32 v91, v4
	v_mov_b32_e32 v84, v4
	v_mov_b32_e32 v85, v4
	v_mov_b32_e32 v86, v4
	v_mov_b32_e32 v87, v4
	v_mov_b32_e32 v104, v4
	v_mov_b32_e32 v105, v4
	v_mov_b32_e32 v106, v4
	v_mov_b32_e32 v107, v4
	v_mov_b32_e32 v100, v4
	v_mov_b32_e32 v101, v4
	v_mov_b32_e32 v102, v4
	v_mov_b32_e32 v103, v4
	v_mov_b32_e32 v120, v4
	v_mov_b32_e32 v121, v4
	v_mov_b32_e32 v122, v4
	v_mov_b32_e32 v123, v4
	v_mov_b32_e32 v116, v4
	v_mov_b32_e32 v117, v4
	v_mov_b32_e32 v118, v4
	v_mov_b32_e32 v119, v4
	v_mov_b32_e32 v80, v4
	v_mov_b32_e32 v81, v4
	v_mov_b32_e32 v82, v4
	v_mov_b32_e32 v83, v4
	v_mov_b32_e32 v76, v4
	v_mov_b32_e32 v77, v4
	v_mov_b32_e32 v78, v4
	v_mov_b32_e32 v79, v4
	v_mov_b32_e32 v96, v4
	v_mov_b32_e32 v97, v4
	v_mov_b32_e32 v98, v4
	v_mov_b32_e32 v99, v4
	v_mov_b32_e32 v92, v4
	v_mov_b32_e32 v93, v4
	v_mov_b32_e32 v94, v4
	v_mov_b32_e32 v95, v4
	v_mov_b32_e32 v112, v4
	v_mov_b32_e32 v113, v4
	v_mov_b32_e32 v114, v4
	v_mov_b32_e32 v115, v4
	v_mov_b32_e32 v108, v4
	v_mov_b32_e32 v109, v4
	v_mov_b32_e32 v110, v4
	v_mov_b32_e32 v111, v4
	v_mov_b32_e32 v128, v4
	v_mov_b32_e32 v129, v4
	v_mov_b32_e32 v130, v4
	v_mov_b32_e32 v131, v4
	v_mov_b32_e32 v124, v4
	v_mov_b32_e32 v125, v4
	v_mov_b32_e32 v126, v4
	v_mov_b32_e32 v127, v4
	s_add_u32 s18, s14, 0xfff80080
	s_addc_u32 s19, s15, -1
	s_add_i32 s55, 0, 0x10000
	v_add_u32_e32 v157, s55, v140
	s_branch .LBB0_332

; #define PG8_STAGE(bufoff, gbase, voff) do { _Pragma("unroll") for (int _i = 0; _i < 2; ++_i) \
;         __builtin_amdgcn_global_load_lds((const unsigned*)((const char*)(gbase) + (voff)[_i]), (LAS unsigned*)(lds + (bufoff) + ldsw + _i * 8192), 16, 0, 0); } while (0)
; #define PG8_LDA(dst, b, h) do { _Pragma("unroll") for (int m = 0; m < 4; ++m) _Pragma("unroll") for (int k = 0; k < 2; ++k) dst[m][k] = *(const LAS h8*)(lds + PG8_SA(b, h) + aoff + m * 2048 + k * 1024); } while (0)
; #define PG8_LDB(dst, b, h) do { _Pragma("unroll") for (int n = 0; n < 2; ++n) _Pragma("unroll") for (int k = 0; k < 2; ++k) dst[n][k] = *(const LAS h8*)(lds + PG8_SB(b, h) + boff + n * 2048 + k * 1024); } while (0)
; #define PG8_WAIT_V(n) asm volatile("s_waitcnt vmcnt(" #n ")" ::: "memory")
; #define PG8_WAIT_L(n) asm volatile("s_waitcnt lgkmcnt(" #n ")" ::: "memory")
; #define PG8_BAR __builtin_amdgcn_s_barrier()
; #define PG8_SCHED __builtin_amdgcn_sched_barrier(0)
; template <class Epi>
; __device__ __forceinline__ void gemm_phase(LAS unsigned char* lds, const Gemm g, const StaticOrder& S, const Epi& E, const int tid) {
;     ...
;         for (int t = 0; t < nt; t += 2) {
;             const bool last = (t == nt - 2);
;             const char* a1 = cA + (size_t)(t + 1) * kstep;
;             const char* a2 = last ? nA : cA + (size_t)(t + 2) * kstep; const char* b2 = last ? nB : cB + (size_t)(t + 2) * kstep;
;             const char* a3 = a2 + kstep; const char* b3 = b2 + kstep;
;             if constexpr (Epi::HAS_MID) { if (t == (nt >> 1)) E.mid(acc, cur, wr, wc, fr, fq); }
;             PG8_LDB(B0, 0, 0); PG8_SCHED; PG8_LDA(At, 0, 0); PG8_STAGE(PG8_SA(1, 1), a1 + hstep, voffA);
;             PG8_WAIT_L(8); PG8_BAR; PG8_WAIT_L(0); PG8_MMA(0, 0, At, B0); PG8_BAR; PG8_SCHED;
;             PG8_LDB(B1, 0, 1); PG8_STAGE(PG8_SB(0, 0), b2, voffB);
;             PG8_BAR; PG8_WAIT_L(0); PG8_MMA(0, 1, At, B1); PG8_BAR;
;             PG8_LDA(At, 0, 1); PG8_STAGE(PG8_SA(0, 0), a2, voffA);
;             PG8_BAR; PG8_WAIT_L(0); PG8_MMA(1, 0, At, B0); PG8_BAR; PG8_SCHED;
;             PG8_STAGE(PG8_SB(0, 1), b2 + hstepB, voffB);
;             PG8_WAIT_V(6); PG8_BAR; PG8_MMA(1, 1, At, B1); PG8_BAR;
.LBB0_332:
	ds_read_b128 v[144:147], v157
	ds_read_b128 v[162:165], v157 offset:1024
	ds_read_b128 v[166:169], v157 offset:2048
	ds_read_b128 v[170:173], v157 offset:3072
	s_cmp_eq_u32 s54, 28
	s_cselect_b32 s23, s9, s19
	s_cselect_b32 s22, s50, s18
	s_cselect_b32 s19, s1, s53
	s_cselect_b32 s18, s51, s52
	s_add_i32 m0, s39, 0xc000
	ds_read_b128 v[174:177], v143
	ds_read_b128 v[190:193], v143 offset:1024
	ds_read_b128 v[194:197], v143 offset:2048
	ds_read_b128 v[198:201], v143 offset:3072
	ds_read_b128 v[202:205], v143 offset:4096
	ds_read_b128 v[206:209], v143 offset:5120
	ds_read_b128 v[210:213], v143 offset:6144
	ds_read_b128 v[214:217], v143 offset:7168
	global_load_lds_dwordx4 v136, s[14:15]
	s_add_i32 m0, s39, 0xe000
	s_nop 0
	global_load_lds_dwordx4 v138, s[14:15]
	s_waitcnt lgkmcnt(8)
	s_barrier
	s_waitcnt lgkmcnt(0)
	s_waitcnt lgkmcnt(0)
	v_mfma_f32_16x16x32_bf16 v[124:127], v[144:147], v[174:177], v[124:127]
	v_mfma_f32_16x16x32_bf16 v[128:131], v[166:169], v[174:177], v[128:131]
	v_mfma_f32_16x16x32_bf16 v[108:111], v[144:147], v[194:197], v[108:111]
	v_mfma_f32_16x16x32_bf16 v[112:115], v[166:169], v[194:197], v[112:115]
	v_mfma_f32_16x16x32_bf16 v[92:95], v[144:147], v[202:205], v[92:95]
	v_mfma_f32_16x16x32_bf16 v[96:99], v[166:169], v[202:205], v[96:99]
	v_mfma_f32_16x16x32_bf16 v[76:79], v[144:147], v[210:213], v[76:79]
	v_mfma_f32_16x16x32_bf16 v[80:83], v[166:169], v[210:213], v[80:83]
	v_mfma_f32_16x16x32_bf16 v[124:127], v[162:165], v[190:193], v[124:127]
	v_mfma_f32_16x16x32_bf16 v[128:131], v[170:173], v[190:193], v[128:131]
	v_mfma_f32_16x16x32_bf16 v[108:111], v[162:165], v[198:201], v[108:111]
	v_mfma_f32_16x16x32_bf16 v[112:115], v[170:173], v[198:201], v[112:115]
	v_mfma_f32_16x16x32_bf16 v[92:95], v[162:165], v[206:209], v[92:95]
	v_mfma_f32_16x16x32_bf16 v[96:99], v[170:173], v[206:209], v[96:99]
	v_mfma_f32_16x16x32_bf16 v[76:79], v[162:165], v[214:217], v[76:79]
	v_mfma_f32_16x16x32_bf16 v[80:83], v[170:173], v[214:217], v[80:83]
	s_add_i32 s58, 0, 0x14000
	s_add_i32 s55, s55, s38
	v_add_u32_e32 v157, s58, v140
	v_lshl_add_u64 v[178:179], s[18:19], 0, v[2:3]
	s_mov_b32 m0, s55
	s_barrier
	ds_read_b128 v[218:221], v157
	ds_read_b128 v[222:225], v157 offset:1024
	ds_read_b128 v[226:229], v157 offset:2048
	ds_read_b128 v[230:233], v157 offset:3072
	global_load_lds_dwordx4 v[178:179], off
	v_lshl_add_u64 v[234:235], s[18:19], 0, v[0:1]
	s_add_i32 m0, s55, 0x2000
	s_nop 0
	global_load_lds_dwordx4 v[234:235], off
	s_barrier
	s_waitcnt lgkmcnt(0)
	s_waitcnt lgkmcnt(0)
	v_mfma_f32_16x16x32_bf16 v[116:119], v[218:221], v[174:177], v[116:119]
	v_mfma_f32_16x16x32_bf16 v[120:123], v[226:229], v[174:177], v[120:123]
	v_mfma_f32_16x16x32_bf16 v[100:103], v[218:221], v[194:197], v[100:103]
	v_mfma_f32_16x16x32_bf16 v[104:107], v[226:229], v[194:197], v[104:107]
	v_mfma_f32_16x16x32_bf16 v[84:87], v[218:221], v[202:205], v[84:87]
	v_mfma_f32_16x16x32_bf16 v[88:91], v[226:229], v[202:205], v[88:91]
	v_mfma_f32_16x16x32_bf16 v[68:71], v[218:221], v[210:213], v[68:71]
	v_mfma_f32_16x16x32_bf16 v[72:75], v[226:229], v[210:213], v[72:75]
	v_mfma_f32_16x16x32_bf16 v[116:119], v[222:225], v[190:193], v[116:119]
	v_mfma_f32_16x16x32_bf16 v[120:123], v[230:233], v[190:193], v[120:123]
	v_mfma_f32_16x16x32_bf16 v[100:103], v[222:225], v[198:201], v[100:103]
	v_mfma_f32_16x16x32_bf16 v[104:107], v[230:233], v[198:201], v[104:107]
	v_mfma_f32_16x16x32_bf16 v[84:87], v[222:225], v[206:209], v[84:87]
	v_mfma_f32_16x16x32_bf16 v[88:91], v[230:233], v[206:209], v[88:91]
	v_mfma_f32_16x16x32_bf16 v[68:71], v[222:225], v[214:217], v[68:71]
	v_mfma_f32_16x16x32_bf16 v[72:75], v[230:233], v[214:217], v[72:75]
	s_mov_b32 m0, s39
	v_lshl_add_u64 v[236:237], s[22:23], 0, v[134:135]
	s_barrier
	ds_read_b128 v[174:177], v143 offset:16384
	ds_read_b128 v[190:193], v143 offset:17408
	ds_read_b128 v[194:197], v143 offset:18432
	ds_read_b128 v[198:201], v143 offset:19456
	ds_read_b128 v[202:205], v143 offset:20480
	ds_read_b128 v[206:209], v143 offset:21504
	ds_read_b128 v[210:213], v143 offset:22528
	ds_read_b128 v[214:217], v143 offset:23552
	global_load_lds_dwordx4 v[236:237], off
	v_lshl_add_u64 v[238:239], s[22:23], 0, v[132:133]
	s_mov_b32 m0, s40
	s_nop 0
	global_load_lds_dwordx4 v[238:239], off
	s_barrier
	s_waitcnt lgkmcnt(0)
	s_waitcnt lgkmcnt(0)
	v_mfma_f32_16x16x32_bf16 v[60:63], v[144:147], v[174:177], v[60:63]
	v_mfma_f32_16x16x32_bf16 v[64:67], v[166:169], v[174:177], v[64:67]
	v_mfma_f32_16x16x32_bf16 v[44:47], v[144:147], v[194:197], v[44:47]
	v_mfma_f32_16x16x32_bf16 v[48:51], v[166:169], v[194:197], v[48:51]
	v_mfma_f32_16x16x32_bf16 v[28:31], v[144:147], v[202:205], v[28:31]
	v_mfma_f32_16x16x32_bf16 v[32:35], v[166:169], v[202:205], v[32:35]
	v_mfma_f32_16x16x32_bf16 v[12:15], v[144:147], v[210:213], v[12:15]
	v_mfma_f32_16x16x32_bf16 v[16:19], v[166:169], v[210:213], v[16:19]
	v_mfma_f32_16x16x32_bf16 v[60:63], v[162:165], v[190:193], v[60:63]
	v_mfma_f32_16x16x32_bf16 v[64:67], v[170:173], v[190:193], v[64:67]
	v_mfma_f32_16x16x32_bf16 v[44:47], v[162:165], v[198:201], v[44:47]
	v_mfma_f32_16x16x32_bf16 v[48:51], v[170:173], v[198:201], v[48:51]
	v_mfma_f32_16x16x32_bf16 v[28:31], v[162:165], v[206:209], v[28:31]
	v_mfma_f32_16x16x32_bf16 v[32:35], v[170:173], v[206:209], v[32:35]
	v_mfma_f32_16x16x32_bf16 v[12:15], v[162:165], v[214:217], v[12:15]
	v_mfma_f32_16x16x32_bf16 v[16:19], v[170:173], v[214:217], v[16:19]
	s_barrier
	s_add_u32 s56, s18, 0x20000
	s_addc_u32 s57, s19, 0
	s_add_i32 s55, s58, s38
	s_mov_b32 m0, s55
	s_nop 0
	global_load_lds_dwordx4 v2, s[56:57]
	s_add_i32 m0, s55, 0x2000
	s_nop 0
	global_load_lds_dwordx4 v0, s[56:57]
	s_waitcnt vmcnt(6)
	s_barrier
; #define PG8_STAGE(bufoff, gbase, voff) do { _Pragma("unroll") for (int _i = 0; _i < 2; ++_i) \
;         __builtin_amdgcn_global_load_lds((const unsigned*)((const char*)(gbase) + (voff)[_i]), (LAS unsigned*)(lds + (bufoff) + ldsw + _i * 8192), 16, 0, 0); } while (0)
; #define PG8_LDA(dst, b, h) do { _Pragma("unroll") for (int m = 0; m < 4; ++m) _Pragma("unroll") for (int k = 0; k < 2; ++k) dst[m][k] = *(const LAS h8*)(lds + PG8_SA(b, h) + aoff + m * 2048 + k * 1024); } while (0)
; #define PG8_LDB(dst, b, h) do { _Pragma("unroll") for (int n = 0; n < 2; ++n) _Pragma("unroll") for (int k = 0; k < 2; ++k) dst[n][k] = *(const LAS h8*)(lds + PG8_SB(b, h) + boff + n * 2048 + k * 1024); } while (0)
; #define PG8_WAIT_V(n) asm volatile("s_waitcnt vmcnt(" #n ")" ::: "memory")
; #define PG8_WAIT_L(n) asm volatile("s_waitcnt lgkmcnt(" #n ")" ::: "memory")
; #define PG8_BAR __builtin_amdgcn_s_barrier()
; #define PG8_SCHED __builtin_amdgcn_sched_barrier(0)
; template <class Epi>
; __device__ __forceinline__ void gemm_phase(LAS unsigned char* lds, const Gemm g, const StaticOrder& S, const Epi& E, const int tid) {
;     ...
;             PG8_WAIT_V(6); PG8_BAR; PG8_MMA(1, 1, At, B1); PG8_BAR;
;             PG8_LDB(B0, 1, 0); PG8_SCHED; PG8_LDA(At, 1, 0); PG8_STAGE(PG8_SA(0, 1), a2 + hstep, voffA);
;             PG8_WAIT_L(8); PG8_BAR; PG8_WAIT_L(0); PG8_MMA(0, 0, At, B0); PG8_BAR; PG8_SCHED;
;             PG8_LDB(B1, 1, 1); PG8_STAGE(PG8_SB(1, 0), b3, voffB);
;             PG8_BAR; PG8_WAIT_L(0); PG8_MMA(0, 1, At, B1); PG8_BAR;
;             PG8_LDA(At, 1, 1); PG8_STAGE(PG8_SA(1, 0), a3, voffA);
	v_mfma_f32_16x16x32_bf16 v[52:55], v[218:221], v[174:177], v[52:55]
	v_mfma_f32_16x16x32_bf16 v[56:59], v[226:229], v[174:177], v[56:59]
	v_mfma_f32_16x16x32_bf16 v[36:39], v[218:221], v[194:197], v[36:39]
	v_mfma_f32_16x16x32_bf16 v[40:43], v[226:229], v[194:197], v[40:43]
	v_mfma_f32_16x16x32_bf16 v[20:23], v[218:221], v[202:205], v[20:23]
	v_mfma_f32_16x16x32_bf16 v[24:27], v[226:229], v[202:205], v[24:27]
	v_mfma_f32_16x16x32_bf16 v[8:11], v[218:221], v[210:213], v[8:11]
	v_mfma_f32_16x16x32_bf16 v[4:7], v[226:229], v[210:213], v[4:7]
	v_mfma_f32_16x16x32_bf16 v[52:55], v[222:225], v[190:193], v[52:55]
	v_mfma_f32_16x16x32_bf16 v[56:59], v[230:233], v[190:193], v[56:59]
	v_mfma_f32_16x16x32_bf16 v[36:39], v[222:225], v[198:201], v[36:39]
	v_mfma_f32_16x16x32_bf16 v[40:43], v[230:233], v[198:201], v[40:43]
	v_mfma_f32_16x16x32_bf16 v[20:23], v[222:225], v[206:209], v[20:23]
	v_mfma_f32_16x16x32_bf16 v[24:27], v[230:233], v[206:209], v[24:27]
	v_mfma_f32_16x16x32_bf16 v[8:11], v[222:225], v[214:217], v[8:11]
	v_mfma_f32_16x16x32_bf16 v[4:7], v[230:233], v[214:217], v[4:7]
	s_add_i32 s55, 0, 0x18000
	v_add_u32_e32 v157, s55, v140
	s_barrier
	ds_read_b128 v[144:147], v157
	ds_read_b128 v[162:165], v157 offset:1024
	ds_read_b128 v[166:169], v157 offset:2048
	ds_read_b128 v[170:173], v157 offset:3072
	s_add_u32 s22, s22, 0x80000
	s_addc_u32 s23, s23, 0
	s_mov_b32 m0, s41
	ds_read_b128 v[174:177], v143 offset:32768
	ds_read_b128 v[190:193], v143 offset:33792
	ds_read_b128 v[194:197], v143 offset:34816
	ds_read_b128 v[198:201], v143 offset:35840
	ds_read_b128 v[202:205], v143 offset:36864
	ds_read_b128 v[206:209], v143 offset:37888
	ds_read_b128 v[210:213], v143 offset:38912
	ds_read_b128 v[214:217], v143 offset:39936
	global_load_lds_dwordx4 v134, s[22:23]
	s_mov_b32 m0, s42
	s_nop 0
	global_load_lds_dwordx4 v132, s[22:23]
	s_waitcnt lgkmcnt(8)
	s_barrier
	s_waitcnt lgkmcnt(0)
	s_waitcnt lgkmcnt(0)
	v_mfma_f32_16x16x32_bf16 v[124:127], v[144:147], v[174:177], v[124:127]
	v_mfma_f32_16x16x32_bf16 v[128:131], v[166:169], v[174:177], v[128:131]
	v_mfma_f32_16x16x32_bf16 v[108:111], v[144:147], v[194:197], v[108:111]
	v_mfma_f32_16x16x32_bf16 v[112:115], v[166:169], v[194:197], v[112:115]
	v_mfma_f32_16x16x32_bf16 v[92:95], v[144:147], v[202:205], v[92:95]
	v_mfma_f32_16x16x32_bf16 v[96:99], v[166:169], v[202:205], v[96:99]
	v_mfma_f32_16x16x32_bf16 v[76:79], v[144:147], v[210:213], v[76:79]
	v_mfma_f32_16x16x32_bf16 v[80:83], v[166:169], v[210:213], v[80:83]
	v_mfma_f32_16x16x32_bf16 v[124:127], v[162:165], v[190:193], v[124:127]
	v_mfma_f32_16x16x32_bf16 v[128:131], v[170:173], v[190:193], v[128:131]
	v_mfma_f32_16x16x32_bf16 v[108:111], v[162:165], v[198:201], v[108:111]
	v_mfma_f32_16x16x32_bf16 v[112:115], v[170:173], v[198:201], v[112:115]
	v_mfma_f32_16x16x32_bf16 v[92:95], v[162:165], v[206:209], v[92:95]
	v_mfma_f32_16x16x32_bf16 v[96:99], v[170:173], v[206:209], v[96:99]
	v_mfma_f32_16x16x32_bf16 v[76:79], v[162:165], v[214:217], v[76:79]
	v_mfma_f32_16x16x32_bf16 v[80:83], v[170:173], v[214:217], v[80:83]
	s_add_i32 s22, 0, 0x1c000
	s_add_i32 s23, s55, s38
	v_add_u32_e32 v157, s22, v140
	v_lshl_add_u64 v[178:179], v[178:179], 0, s[30:31]
	s_mov_b32 m0, s23
	s_barrier
	ds_read_b128 v[218:221], v157
	ds_read_b128 v[222:225], v157 offset:1024
	ds_read_b128 v[226:229], v157 offset:2048
	ds_read_b128 v[230:233], v157 offset:3072
	global_load_lds_dwordx4 v[178:179], off
	v_lshl_add_u64 v[178:179], v[234:235], 0, s[30:31]
	s_add_i32 m0, s23, 0x2000
	s_nop 0
	global_load_lds_dwordx4 v[178:179], off
	s_barrier
	s_waitcnt lgkmcnt(0)
	s_waitcnt lgkmcnt(0)
	v_mfma_f32_16x16x32_bf16 v[116:119], v[218:221], v[174:177], v[116:119]
	v_mfma_f32_16x16x32_bf16 v[120:123], v[226:229], v[174:177], v[120:123]
	v_mfma_f32_16x16x32_bf16 v[100:103], v[218:221], v[194:197], v[100:103]
	v_mfma_f32_16x16x32_bf16 v[104:107], v[226:229], v[194:197], v[104:107]
	v_mfma_f32_16x16x32_bf16 v[84:87], v[218:221], v[202:205], v[84:87]
	v_mfma_f32_16x16x32_bf16 v[88:91], v[226:229], v[202:205], v[88:91]
	v_mfma_f32_16x16x32_bf16 v[68:71], v[218:221], v[210:213], v[68:71]
	v_mfma_f32_16x16x32_bf16 v[72:75], v[226:229], v[210:213], v[72:75]
	v_mfma_f32_16x16x32_bf16 v[116:119], v[222:225], v[190:193], v[116:119]
	v_mfma_f32_16x16x32_bf16 v[120:123], v[230:233], v[190:193], v[120:123]
	v_mfma_f32_16x16x32_bf16 v[100:103], v[222:225], v[198:201], v[100:103]
	v_mfma_f32_16x16x32_bf16 v[104:107], v[230:233], v[198:201], v[104:107]
	v_mfma_f32_16x16x32_bf16 v[84:87], v[222:225], v[206:209], v[84:87]
	v_mfma_f32_16x16x32_bf16 v[88:91], v[230:233], v[206:209], v[88:91]
	v_mfma_f32_16x16x32_bf16 v[68:71], v[222:225], v[214:217], v[68:71]
	v_mfma_f32_16x16x32_bf16 v[72:75], v[230:233], v[214:217], v[72:75]
	s_mov_b32 m0, s43
	v_lshl_add_u64 v[178:179], v[236:237], 0, s[30:31]
	s_barrier
	ds_read_b128 v[174:177], v143 offset:49152
	ds_read_b128 v[190:193], v143 offset:50176
	ds_read_b128 v[194:197], v143 offset:51200
	ds_read_b128 v[198:201], v143 offset:52224
	ds_read_b128 v[202:205], v143 offset:53248
	ds_read_b128 v[206:209], v143 offset:54272
	ds_read_b128 v[210:213], v143 offset:55296
	ds_read_b128 v[214:217], v143 offset:56320
	global_load_lds_dwordx4 v[178:179], off
	v_lshl_add_u64 v[178:179], v[238:239], 0, s[30:31]
	s_mov_b32 m0, s46
	s_nop 0
	global_load_lds_dwordx4 v[178:179], off
	s_barrier
; #define PG8_STAGE(bufoff, gbase, voff) do { _Pragma("unroll") for (int _i = 0; _i < 2; ++_i) \
;         __builtin_amdgcn_global_load_lds((const unsigned*)((const char*)(gbase) + (voff)[_i]), (LAS unsigned*)(lds + (bufoff) + ldsw + _i * 8192), 16, 0, 0); } while (0)
; #define PG8_LDA(dst, b, h) do { _Pragma("unroll") for (int m = 0; m < 4; ++m) _Pragma("unroll") for (int k = 0; k < 2; ++k) dst[m][k] = *(const LAS h8*)(lds + PG8_SA(b, h) + aoff + m * 2048 + k * 1024); } while (0)
; #define PG8_WAIT_V(n) asm volatile("s_waitcnt vmcnt(" #n ")" ::: "memory")
; #define PG8_WAIT_L(n) asm volatile("s_waitcnt lgkmcnt(" #n ")" ::: "memory")
; #define PG8_BAR __builtin_amdgcn_s_barrier()
; #define PG8_SCHED __builtin_amdgcn_sched_barrier(0)
; template <class Epi>
; __device__ __forceinline__ void gemm_phase(LAS unsigned char* lds, const Gemm g, const StaticOrder& S, const Epi& E, const int tid) {
;     ...
;             PG8_LDA(At, 1, 1); PG8_STAGE(PG8_SA(1, 0), a3, voffA);
;             PG8_BAR; PG8_WAIT_L(0); PG8_MMA(1, 0, At, B0); PG8_BAR; PG8_SCHED;
;             PG8_STAGE(PG8_SB(1, 1), b3 + hstepB, voffB);
;             PG8_WAIT_V(6); PG8_BAR; PG8_MMA(1, 1, At, B1); PG8_BAR;
;         }
;     __device__ __forceinline__ void operator()(f32x4 (&acc)[2][2][4][2], const pg8::Unit& u, int wr, int wc, int fr, int fq) const {
;         const bool hi = fr >= 8;
;         const int row0 = u.pm * 256 + wr * 64 + (fr & 7), col = u.pn * 256 + wc * 64 + fq * 8 + (hi ? 32 : 0);
; #pragma unroll
;         for (int ai = 0; ai < 2; ++ai)
; #pragma unroll
;             for (int m = 0; m < 4; ++m) {
;                 const h8 x0 = pack8(acc[ai][0][m][0], acc[ai][0][m][1]), x1 = pack8(acc[ai][1][m][0], acc[ai][1][m][1]);
;                 const i32x4 snd = hi ? __builtin_bit_cast(i32x4, x0) : __builtin_bit_cast(i32x4, x1);
;                 i32x4 rcv;
; #pragma unroll
;                 for (int d = 0; d < 4; ++d) rcv[d] = __builtin_amdgcn_update_dpp(0, snd[d], 0x128  , 0xF, 0xF, false);
;                 const h8 rv = __builtin_bit_cast(h8, rcv);
;                 const h8 vA = hi ? rv : x0;
;                 const h8 vB = hi ? x1 : rv;
;                 half_t* rowp = O + (size_t)(row0 + ai * 128 + m * 16) * NIN + col;
;                 __builtin_nontemporal_store(vA, (h8*)rowp); __builtin_nontemporal_store(vB, (h8*)(rowp + (size_t)8 * NIN)); }
	s_waitcnt lgkmcnt(0)
	s_waitcnt lgkmcnt(0)
	v_mfma_f32_16x16x32_bf16 v[60:63], v[144:147], v[174:177], v[60:63]
	v_mfma_f32_16x16x32_bf16 v[64:67], v[166:169], v[174:177], v[64:67]
	v_mfma_f32_16x16x32_bf16 v[44:47], v[144:147], v[194:197], v[44:47]
	v_mfma_f32_16x16x32_bf16 v[48:51], v[166:169], v[194:197], v[48:51]
	v_mfma_f32_16x16x32_bf16 v[28:31], v[144:147], v[202:205], v[28:31]
	v_mfma_f32_16x16x32_bf16 v[32:35], v[166:169], v[202:205], v[32:35]
	v_mfma_f32_16x16x32_bf16 v[12:15], v[144:147], v[210:213], v[12:15]
	v_mfma_f32_16x16x32_bf16 v[16:19], v[166:169], v[210:213], v[16:19]
	v_mfma_f32_16x16x32_bf16 v[60:63], v[162:165], v[190:193], v[60:63]
	v_mfma_f32_16x16x32_bf16 v[64:67], v[170:173], v[190:193], v[64:67]
	v_mfma_f32_16x16x32_bf16 v[44:47], v[162:165], v[198:201], v[44:47]
	v_mfma_f32_16x16x32_bf16 v[48:51], v[170:173], v[198:201], v[48:51]
	v_mfma_f32_16x16x32_bf16 v[28:31], v[162:165], v[206:209], v[28:31]
	v_mfma_f32_16x16x32_bf16 v[32:35], v[170:173], v[206:209], v[32:35]
	v_mfma_f32_16x16x32_bf16 v[12:15], v[162:165], v[214:217], v[12:15]
	v_mfma_f32_16x16x32_bf16 v[16:19], v[170:173], v[214:217], v[16:19]
	s_barrier
	s_add_u32 s18, s18, 0x20080
	s_addc_u32 s19, s19, 0
	s_add_i32 s22, s22, s38
	s_mov_b32 m0, s22
	s_nop 0
	global_load_lds_dwordx4 v2, s[18:19]
	v_lshl_add_u64 v[144:145], s[18:19], 0, v[0:1]
	s_add_i32 m0, s22, 0x2000
	s_nop 0
	global_load_lds_dwordx4 v[144:145], off
	s_waitcnt vmcnt(6)
	s_barrier
	v_mfma_f32_16x16x32_bf16 v[52:55], v[218:221], v[174:177], v[52:55]
	v_mfma_f32_16x16x32_bf16 v[56:59], v[226:229], v[174:177], v[56:59]
	v_mfma_f32_16x16x32_bf16 v[36:39], v[218:221], v[194:197], v[36:39]
	v_mfma_f32_16x16x32_bf16 v[40:43], v[226:229], v[194:197], v[40:43]
	v_mfma_f32_16x16x32_bf16 v[20:23], v[218:221], v[202:205], v[20:23]
	v_mfma_f32_16x16x32_bf16 v[24:27], v[226:229], v[202:205], v[24:27]
	v_mfma_f32_16x16x32_bf16 v[8:11], v[218:221], v[210:213], v[8:11]
	v_mfma_f32_16x16x32_bf16 v[4:7], v[226:229], v[210:213], v[4:7]
	v_mfma_f32_16x16x32_bf16 v[52:55], v[222:225], v[190:193], v[52:55]
	v_mfma_f32_16x16x32_bf16 v[56:59], v[230:233], v[190:193], v[56:59]
	v_mfma_f32_16x16x32_bf16 v[36:39], v[222:225], v[198:201], v[36:39]
	v_mfma_f32_16x16x32_bf16 v[40:43], v[230:233], v[198:201], v[40:43]
	v_mfma_f32_16x16x32_bf16 v[20:23], v[222:225], v[206:209], v[20:23]
	v_mfma_f32_16x16x32_bf16 v[24:27], v[230:233], v[206:209], v[24:27]
	v_mfma_f32_16x16x32_bf16 v[8:11], v[222:225], v[214:217], v[8:11]
	v_mfma_f32_16x16x32_bf16 v[4:7], v[230:233], v[214:217], v[4:7]
	s_add_i32 s54, s54, 2
	s_add_u32 s14, s14, 0x100
	s_addc_u32 s15, s15, 0
	s_add_u32 s52, s52, 0x100
	s_addc_u32 s53, s53, 0
	s_cmp_gt_u32 s54, 29
	s_cbranch_scc1 .Lproj_exit
	s_add_u32 s18, s14, 0xfff80080
	s_addc_u32 s19, s15, -1
	s_add_i32 s55, 0, 0x10000
	v_add_u32_e32 v157, s55, v140
	s_branch .Lproj_head
.Lproj_exit:
	s_barrier
	v_cvt_pk_f16_f32 v124, v124, v125
	v_cvt_pk_f16_f32 v116, v116, v117
	v_cvt_pk_f16_f32 v130, v130, v131
	v_cvt_pk_f16_f32 v131, v122, v123
	v_cvt_pk_f16_f32 v128, v128, v129
	v_cvt_pk_f16_f32 v129, v120, v121
	v_cvt_pk_f16_f32 v121, v126, v127
	v_cvt_pk_f16_f32 v118, v118, v119
	v_cndmask_b32_e64 v117, v116, v124, s[4:5]
	v_mov_b32_e32 v147, v3
	v_cndmask_b32_e64 v122, v131, v130, s[4:5]
	v_cndmask_b32_e64 v119, v118, v121, s[4:5]
	v_mov_b32_dpp v147, v117 row_ror:8 row_mask:0xf bank_mask:0xf
	v_mov_b32_e32 v117, v3
	v_mov_b32_e32 v125, v3
	v_lshl_or_b32 v144, s48, 8, v142
	v_cndmask_b32_e64 v120, v129, v128, s[4:5]
	v_mov_b32_dpp v117, v119 row_ror:8 row_mask:0xf bank_mask:0xf
	v_mov_b32_e32 v119, v3
	v_mov_b32_dpp v125, v122 row_ror:8 row_mask:0xf bank_mask:0xf
	v_lshl_add_u32 v146, s49, 8, v141
	v_ashrrev_i32_e32 v145, 31, v144
	v_mov_b32_dpp v119, v120 row_ror:8 row_mask:0xf bank_mask:0xf
	v_cndmask_b32_e64 v123, v130, v125, s[4:5]
	v_cndmask_b32_e64 v121, v121, v117, s[4:5]
	v_cndmask_b32_e64 v120, v124, v147, s[4:5]
	v_cndmask_b32_e64 v127, v125, v131, s[4:5]
	v_cndmask_b32_e64 v125, v117, v118, s[4:5]
	v_cndmask_b32_e64 v124, v147, v116, s[4:5]
	v_mov_b64_e32 v[116:117], s[36:37]
	v_cndmask_b32_e64 v122, v128, v119, s[4:5]
	v_cndmask_b32_e64 v126, v119, v129, s[4:5]
	v_mad_i64_i32 v[128:129], s[14:15], v146, s35, v[116:117]
	v_lshlrev_b64 v[118:119], 1, v[144:145]
	v_lshl_add_u64 v[128:129], v[128:129], 0, v[118:119]
	s_mov_b32 s1, 0x3c000
	global_store_dwordx4 v[128:129], v[120:123], off nt
	v_cvt_pk_f16_f32 v112, v112, v113
	v_cvt_pk_f16_f32 v104, v104, v105
	v_add_co_u32_e32 v120, vcc, s1, v128
	v_cvt_pk_f16_f32 v108, v108, v109
	s_nop 0
	v_addc_co_u32_e32 v121, vcc, 0, v129, vcc
	v_cvt_pk_f16_f32 v109, v100, v101
	global_store_dwordx4 v[120:121], v[124:127], off nt
	v_cvt_pk_f16_f32 v114, v114, v115
	v_cvt_pk_f16_f32 v106, v106, v107
	v_cndmask_b32_e64 v105, v104, v112, s[4:5]
	v_cndmask_b32_e64 v100, v109, v108, s[4:5]
	v_mov_b32_e32 v113, v3
	v_mov_b32_e32 v120, v3
	v_cndmask_b32_e64 v107, v106, v114, s[4:5]
	v_cvt_pk_f16_f32 v110, v110, v111
	v_cvt_pk_f16_f32 v111, v102, v103
	v_mov_b32_dpp v113, v100 row_ror:8 row_mask:0xf bank_mask:0xf
	v_mov_b32_dpp v120, v105 row_ror:8 row_mask:0xf bank_mask:0xf
	v_mov_b32_e32 v105, v3
	v_cndmask_b32_e64 v102, v111, v110, s[4:5]
	v_mov_b32_e32 v115, v3
	v_mov_b32_dpp v105, v107 row_ror:8 row_mask:0xf bank_mask:0xf
	v_cndmask_b32_e64 v100, v108, v113, s[4:5]
	v_or_b32_e32 v108, 16, v146
	v_mov_b32_dpp v115, v102 row_ror:8 row_mask:0xf bank_mask:0xf
	v_cndmask_b32_e64 v107, v105, v106, s[4:5]
	v_cndmask_b32_e64 v106, v120, v104, s[4:5]
	v_cndmask_b32_e64 v104, v113, v109, s[4:5]
	v_mad_i64_i32 v[108:109], s[14:15], v108, s35, v[116:117]
;     __device__ __forceinline__ void operator()(f32x4 (&acc)[2][2][4][2], const pg8::Unit& u, int wr, int wc, int fr, int fq) const {
;         const bool hi = fr >= 8;
;         const int row0 = u.pm * 256 + wr * 64 + (fr & 7), col = u.pn * 256 + wc * 64 + fq * 8 + (hi ? 32 : 0);
; #pragma unroll
;         for (int ai = 0; ai < 2; ++ai)
; #pragma unroll
;             for (int m = 0; m < 4; ++m) {
;                 const h8 x0 = pack8(acc[ai][0][m][0], acc[ai][0][m][1]), x1 = pack8(acc[ai][1][m][0], acc[ai][1][m][1]);
;                 const i32x4 snd = hi ? __builtin_bit_cast(i32x4, x0) : __builtin_bit_cast(i32x4, x1);
;                 i32x4 rcv;
; #pragma unroll
;                 for (int d = 0; d < 4; ++d) rcv[d] = __builtin_amdgcn_update_dpp(0, snd[d], 0x128  , 0xF, 0xF, false);
;                 const h8 rv = __builtin_bit_cast(h8, rcv);
;                 const h8 vA = hi ? rv : x0;
;                 const h8 vB = hi ? x1 : rv;
;                 half_t* rowp = O + (size_t)(row0 + ai * 128 + m * 16) * NIN + col;
;                 __builtin_nontemporal_store(vA, (h8*)rowp); __builtin_nontemporal_store(vB, (h8*)(rowp + (size_t)8 * NIN)); }
	v_cndmask_b32_e64 v103, v114, v105, s[4:5]
	v_cndmask_b32_e64 v102, v112, v120, s[4:5]
	v_cndmask_b32_e64 v101, v110, v115, s[4:5]
	v_lshl_add_u64 v[108:109], v[108:109], 0, v[118:119]
	global_store_dwordx4 v[108:109], v[100:103], off nt
	v_cndmask_b32_e64 v105, v115, v111, s[4:5]
	v_cvt_pk_f16_f32 v96, v96, v97
	v_add_co_u32_e32 v100, vcc, s1, v108
	v_cvt_pk_f16_f32 v88, v88, v89
	s_nop 0
	v_addc_co_u32_e32 v101, vcc, 0, v109, vcc
	v_cvt_pk_f16_f32 v92, v92, v93
	v_cvt_pk_f16_f32 v93, v84, v85
	global_store_dwordx4 v[100:101], v[104:107], off nt
	v_cvt_pk_f16_f32 v98, v98, v99
	v_cvt_pk_f16_f32 v90, v90, v91
	v_cndmask_b32_e64 v89, v88, v96, s[4:5]
	v_cndmask_b32_e64 v84, v93, v92, s[4:5]
	v_mov_b32_e32 v97, v3
	v_mov_b32_e32 v100, v3
	v_cndmask_b32_e64 v91, v90, v98, s[4:5]
	v_cvt_pk_f16_f32 v94, v94, v95
	v_cvt_pk_f16_f32 v95, v86, v87
	v_mov_b32_dpp v97, v84 row_ror:8 row_mask:0xf bank_mask:0xf
	v_mov_b32_dpp v100, v89 row_ror:8 row_mask:0xf bank_mask:0xf
	v_mov_b32_e32 v89, v3
	v_cndmask_b32_e64 v86, v95, v94, s[4:5]
	v_mov_b32_e32 v99, v3
	v_mov_b32_dpp v89, v91 row_ror:8 row_mask:0xf bank_mask:0xf
	v_cndmask_b32_e64 v84, v92, v97, s[4:5]
	v_or_b32_e32 v92, 32, v146
	v_mov_b32_dpp v99, v86 row_ror:8 row_mask:0xf bank_mask:0xf
	v_cndmask_b32_e64 v91, v89, v90, s[4:5]
	v_cndmask_b32_e64 v90, v100, v88, s[4:5]
	v_cndmask_b32_e64 v88, v97, v93, s[4:5]
	v_mad_i64_i32 v[92:93], s[14:15], v92, s35, v[116:117]
	v_cndmask_b32_e64 v87, v98, v89, s[4:5]
	v_cndmask_b32_e64 v86, v96, v100, s[4:5]
	v_cndmask_b32_e64 v85, v94, v99, s[4:5]
	v_lshl_add_u64 v[92:93], v[92:93], 0, v[118:119]
	global_store_dwordx4 v[92:93], v[84:87], off nt
	v_cndmask_b32_e64 v89, v99, v95, s[4:5]
	v_cvt_pk_f16_f32 v80, v80, v81
	v_add_co_u32_e32 v84, vcc, s1, v92
	v_cvt_pk_f16_f32 v72, v72, v73
	s_nop 0
	v_addc_co_u32_e32 v85, vcc, 0, v93, vcc
	v_cvt_pk_f16_f32 v76, v76, v77
	v_cvt_pk_f16_f32 v77, v68, v69
	global_store_dwordx4 v[84:85], v[88:91], off nt
	v_cvt_pk_f16_f32 v82, v82, v83
	v_cvt_pk_f16_f32 v74, v74, v75
	v_cndmask_b32_e64 v73, v72, v80, s[4:5]
	v_cndmask_b32_e64 v68, v77, v76, s[4:5]
	v_mov_b32_e32 v81, v3
	v_mov_b32_e32 v84, v3
	v_cndmask_b32_e64 v75, v74, v82, s[4:5]
	v_cvt_pk_f16_f32 v78, v78, v79
	v_cvt_pk_f16_f32 v79, v70, v71
	v_mov_b32_dpp v81, v68 row_ror:8 row_mask:0xf bank_mask:0xf
	v_mov_b32_dpp v84, v73 row_ror:8 row_mask:0xf bank_mask:0xf
	v_mov_b32_e32 v73, v3
	v_cndmask_b32_e64 v70, v79, v78, s[4:5]
	v_mov_b32_e32 v83, v3
	v_mov_b32_dpp v73, v75 row_ror:8 row_mask:0xf bank_mask:0xf
	v_cndmask_b32_e64 v68, v76, v81, s[4:5]
	v_or_b32_e32 v76, 48, v146
	v_mov_b32_dpp v83, v70 row_ror:8 row_mask:0xf bank_mask:0xf
	v_cndmask_b32_e64 v75, v73, v74, s[4:5]
	v_cndmask_b32_e64 v74, v84, v72, s[4:5]
	v_cndmask_b32_e64 v72, v81, v77, s[4:5]
	v_mad_i64_i32 v[76:77], s[14:15], v76, s35, v[116:117]
	v_cndmask_b32_e64 v71, v82, v73, s[4:5]
	v_cndmask_b32_e64 v70, v80, v84, s[4:5]
	v_cndmask_b32_e64 v69, v78, v83, s[4:5]
	v_lshl_add_u64 v[76:77], v[76:77], 0, v[118:119]
	global_store_dwordx4 v[76:77], v[68:71], off nt
	v_cndmask_b32_e64 v73, v83, v79, s[4:5]
	v_cvt_pk_f16_f32 v64, v64, v65
	v_add_co_u32_e32 v68, vcc, s1, v76
	v_cvt_pk_f16_f32 v56, v56, v57
	s_nop 0
	v_addc_co_u32_e32 v69, vcc, 0, v77, vcc
	global_store_dwordx4 v[68:69], v[72:75], off nt
	v_cvt_pk_f16_f32 v66, v66, v67
	v_cvt_pk_f16_f32 v58, v58, v59
	v_cndmask_b32_e64 v57, v56, v64, s[4:5]
	v_cvt_pk_f16_f32 v60, v60, v61
	v_cvt_pk_f16_f32 v61, v52, v53
	v_mov_b32_e32 v69, v3
	v_cndmask_b32_e64 v59, v58, v66, s[4:5]
	v_cvt_pk_f16_f32 v62, v62, v63
	v_cvt_pk_f16_f32 v63, v54, v55
	v_cndmask_b32_e64 v52, v61, v60, s[4:5]
	v_mov_b32_e32 v65, v3
	v_mov_b32_dpp v69, v57 row_ror:8 row_mask:0xf bank_mask:0xf
	v_mov_b32_e32 v57, v3
	v_add_u32_e32 v68, 0x80, v146
	v_cndmask_b32_e64 v54, v63, v62, s[4:5]
	v_mov_b32_dpp v65, v52 row_ror:8 row_mask:0xf bank_mask:0xf
	v_mov_b32_e32 v67, v3
	v_mov_b32_dpp v57, v59 row_ror:8 row_mask:0xf bank_mask:0xf
	v_cndmask_b32_e64 v52, v60, v65, s[4:5]
	v_mov_b32_dpp v67, v54 row_ror:8 row_mask:0xf bank_mask:0xf
	v_cndmask_b32_e64 v59, v57, v58, s[4:5]
	v_cndmask_b32_e64 v58, v69, v56, s[4:5]
	v_cndmask_b32_e64 v56, v65, v61, s[4:5]
	v_mad_i64_i32 v[60:61], s[14:15], v68, s35, v[116:117]
	v_cndmask_b32_e64 v55, v66, v57, s[4:5]
	v_cndmask_b32_e64 v54, v64, v69, s[4:5]
	v_cndmask_b32_e64 v53, v62, v67, s[4:5]
	v_lshl_add_u64 v[60:61], v[60:61], 0, v[118:119]
	global_store_dwordx4 v[60:61], v[52:55], off nt
	v_cndmask_b32_e64 v57, v67, v63, s[4:5]
	v_cvt_pk_f16_f32 v48, v48, v49
	v_add_co_u32_e32 v52, vcc, s1, v60
	v_cvt_pk_f16_f32 v40, v40, v41
	s_nop 0
; #define PG8_WAIT_V(n) asm volatile("s_waitcnt vmcnt(" #n ")" ::: "memory")
; #define PG8_BAR __builtin_amdgcn_s_barrier()
; template <class Epi>
; __device__ __forceinline__ void gemm_phase(LAS unsigned char* lds, const Gemm g, const StaticOrder& S, const Epi& E, const int tid) {
;     ...
;     PG8_WAIT_V(0);
;     if (wr == 0) PG8_BAR;
;     PG8_BAR;
;     __device__ __forceinline__ void operator()(f32x4 (&acc)[2][2][4][2], const pg8::Unit& u, int wr, int wc, int fr, int fq) const {
;     ...
;                 const h8 x0 = pack8(acc[ai][0][m][0], acc[ai][0][m][1]), x1 = pack8(acc[ai][1][m][0], acc[ai][1][m][1]);
;                 const i32x4 snd = hi ? __builtin_bit_cast(i32x4, x0) : __builtin_bit_cast(i32x4, x1);
;                 i32x4 rcv;
; #pragma unroll
;                 for (int d = 0; d < 4; ++d) rcv[d] = __builtin_amdgcn_update_dpp(0, snd[d], 0x128  , 0xF, 0xF, false);
;                 const h8 rv = __builtin_bit_cast(h8, rcv);
;                 const h8 vA = hi ? rv : x0;
;                 const h8 vB = hi ? x1 : rv;
;                 half_t* rowp = O + (size_t)(row0 + ai * 128 + m * 16) * NIN + col;
;                 __builtin_nontemporal_store(vA, (h8*)rowp); __builtin_nontemporal_store(vB, (h8*)(rowp + (size_t)8 * NIN)); }
	v_addc_co_u32_e32 v53, vcc, 0, v61, vcc
	v_cvt_pk_f16_f32 v44, v44, v45
	v_cvt_pk_f16_f32 v45, v36, v37
	global_store_dwordx4 v[52:53], v[56:59], off nt
	v_cvt_pk_f16_f32 v50, v50, v51
	v_cvt_pk_f16_f32 v42, v42, v43
	v_cndmask_b32_e64 v41, v40, v48, s[4:5]
	v_cndmask_b32_e64 v36, v45, v44, s[4:5]
	v_mov_b32_e32 v49, v3
	v_mov_b32_e32 v52, v3
	v_cndmask_b32_e64 v43, v42, v50, s[4:5]
	v_cvt_pk_f16_f32 v46, v46, v47
	v_cvt_pk_f16_f32 v47, v38, v39
	v_mov_b32_dpp v49, v36 row_ror:8 row_mask:0xf bank_mask:0xf
	v_mov_b32_dpp v52, v41 row_ror:8 row_mask:0xf bank_mask:0xf
	v_mov_b32_e32 v41, v3
	v_cndmask_b32_e64 v38, v47, v46, s[4:5]
	v_mov_b32_e32 v51, v3
	v_mov_b32_dpp v41, v43 row_ror:8 row_mask:0xf bank_mask:0xf
	v_cndmask_b32_e64 v36, v44, v49, s[4:5]
	v_add_u32_e32 v44, 0x90, v146
	v_mov_b32_dpp v51, v38 row_ror:8 row_mask:0xf bank_mask:0xf
	v_cndmask_b32_e64 v43, v41, v42, s[4:5]
	v_cndmask_b32_e64 v42, v52, v40, s[4:5]
	v_cndmask_b32_e64 v40, v49, v45, s[4:5]
	v_mad_i64_i32 v[44:45], s[14:15], v44, s35, v[116:117]
	v_cndmask_b32_e64 v39, v50, v41, s[4:5]
	v_cndmask_b32_e64 v38, v48, v52, s[4:5]
	v_cndmask_b32_e64 v37, v46, v51, s[4:5]
	v_lshl_add_u64 v[44:45], v[44:45], 0, v[118:119]
	global_store_dwordx4 v[44:45], v[36:39], off nt
	v_cndmask_b32_e64 v41, v51, v47, s[4:5]
	v_cvt_pk_f16_f32 v32, v32, v33
	v_add_co_u32_e32 v36, vcc, s1, v44
	v_cvt_pk_f16_f32 v24, v24, v25
	s_nop 0
	v_addc_co_u32_e32 v37, vcc, 0, v45, vcc
	v_cvt_pk_f16_f32 v28, v28, v29
	v_cvt_pk_f16_f32 v29, v20, v21
	global_store_dwordx4 v[36:37], v[40:43], off nt
	v_cvt_pk_f16_f32 v34, v34, v35
	v_cvt_pk_f16_f32 v26, v26, v27
	v_cndmask_b32_e64 v25, v24, v32, s[4:5]
	v_cndmask_b32_e64 v20, v29, v28, s[4:5]
	v_mov_b32_e32 v33, v3
	v_mov_b32_e32 v36, v3
	v_cndmask_b32_e64 v27, v26, v34, s[4:5]
	v_cvt_pk_f16_f32 v30, v30, v31
	v_cvt_pk_f16_f32 v31, v22, v23
	v_mov_b32_dpp v33, v20 row_ror:8 row_mask:0xf bank_mask:0xf
	v_mov_b32_dpp v36, v25 row_ror:8 row_mask:0xf bank_mask:0xf
	v_mov_b32_e32 v25, v3
	v_cvt_pk_f16_f32 v16, v16, v17
	v_cvt_pk_f16_f32 v17, v4, v5
	v_cvt_pk_f16_f32 v5, v14, v15
	v_cvt_pk_f16_f32 v14, v10, v11
	v_cvt_pk_f16_f32 v10, v12, v13
	v_cvt_pk_f16_f32 v8, v8, v9
	v_cndmask_b32_e64 v22, v31, v30, s[4:5]
	v_mov_b32_e32 v35, v3
	v_mov_b32_dpp v25, v27 row_ror:8 row_mask:0xf bank_mask:0xf
	v_cndmask_b32_e64 v20, v28, v33, s[4:5]
	v_add_u32_e32 v28, 0xa0, v146
	v_cndmask_b32_e64 v9, v8, v10, s[4:5]
	v_mov_b32_e32 v12, v3
	v_mov_b32_dpp v35, v22 row_ror:8 row_mask:0xf bank_mask:0xf
	v_cndmask_b32_e64 v27, v25, v26, s[4:5]
	v_cndmask_b32_e64 v26, v36, v24, s[4:5]
	v_cndmask_b32_e64 v24, v33, v29, s[4:5]
	v_mad_i64_i32 v[28:29], s[14:15], v28, s35, v[116:117]
	v_cvt_pk_f16_f32 v18, v18, v19
	v_cvt_pk_f16_f32 v19, v6, v7
	v_cndmask_b32_e64 v4, v17, v16, s[4:5]
	v_mov_b32_dpp v12, v9 row_ror:8 row_mask:0xf bank_mask:0xf
	v_mov_b32_e32 v13, v3
	v_cndmask_b32_e64 v23, v34, v25, s[4:5]
	v_cndmask_b32_e64 v22, v32, v36, s[4:5]
	v_cndmask_b32_e64 v21, v30, v35, s[4:5]
	v_lshl_add_u64 v[28:29], v[28:29], 0, v[118:119]
	v_cndmask_b32_e64 v6, v19, v18, s[4:5]
	v_cndmask_b32_e64 v7, v14, v5, s[4:5]
	v_mov_b32_e32 v9, v3
	v_mov_b32_dpp v13, v4 row_ror:8 row_mask:0xf bank_mask:0xf
	v_mov_b32_e32 v11, v3
	v_cndmask_b32_e64 v4, v10, v12, s[4:5]
	v_cndmask_b32_e64 v8, v12, v8, s[4:5]
	v_add_u32_e32 v12, 0xb0, v146
	global_store_dwordx4 v[28:29], v[20:23], off nt
	v_mov_b32_dpp v9, v7 row_ror:8 row_mask:0xf bank_mask:0xf
	v_mov_b32_dpp v11, v6 row_ror:8 row_mask:0xf bank_mask:0xf
	v_add_co_u32_e32 v20, vcc, s1, v28
	v_cndmask_b32_e64 v6, v16, v13, s[4:5]
	v_cndmask_b32_e64 v10, v13, v17, s[4:5]
	v_mad_i64_i32 v[12:13], s[14:15], v12, s35, v[116:117]
	v_addc_co_u32_e32 v21, vcc, 0, v29, vcc
	v_cndmask_b32_e64 v7, v18, v11, s[4:5]
	v_cndmask_b32_e64 v5, v5, v9, s[4:5]
	v_lshl_add_u64 v[12:13], v[12:13], 0, v[118:119]
	global_store_dwordx4 v[12:13], v[4:7], off nt
	v_cndmask_b32_e64 v25, v35, v31, s[4:5]
	v_cndmask_b32_e64 v11, v11, v19, s[4:5]
	v_add_co_u32_e32 v4, vcc, 0x3c000, v12
	v_cndmask_b32_e64 v9, v9, v14, s[4:5]
	s_nop 0
	v_addc_co_u32_e32 v5, vcc, 0, v13, vcc
	s_and_b64 vcc, exec, s[6:7]
	s_mov_b32 s48, s0
	s_mov_b32 s49, s8
	s_mov_b64 s[18:19], s[12:13]
	s_mov_b64 s[14:15], s[10:11]
	global_store_dwordx4 v[20:21], v[24:27], off nt
	global_store_dwordx4 v[4:5], v[8:11], off nt
	s_cbranch_vccz .LBB0_329
	s_waitcnt vmcnt(0)
	v_readlane_b32 s42, v251, 7
	v_readlane_b32 s46, v251, 9
	v_readlane_b32 s48, v251, 13
	s_cmpk_gt_u32 s20, 0xff
	v_readlane_b32 s43, v251, 8
	v_readlane_b32 s47, v251, 10
	v_readlane_b32 s49, v251, 14
	s_cbranch_scc1 .LBB0_336
	s_barrier
